# conv_gu: the 8 waves of a workgroup load their 64x256 source tile row-wise (1 KB of one row per load) into each other's LDS slices, two workgroup barriers per item
# speedup vs baseline: 1.0069x; 1.0059x over previous
.LBB0_63:
	s_or_b64 exec, exec, s[82:83]
	s_xor_b64 s[82:83], s[80:81], -1
	s_andn2_b64 vcc, exec, s[76:77]
	s_waitcnt lgkmcnt(0)
	s_barrier
	s_cbranch_vccnz .LBB0_7
	v_readlane_b32 s8, v254, 0
	s_and_b64 s[40:41], s[80:81], exec
	v_readlane_b32 s9, v254, 1
	v_readlane_b32 s10, v254, 2
	v_readlane_b32 s11, v254, 3
	s_cselect_b32 s41, s9, s11
	s_cselect_b32 s42, s8, s10
	v_readlane_b32 s8, v254, 52
	v_readlane_b32 s9, v254, 53
	s_cselect_b32 s40, 0, 0x80
	s_lshl_b32 s43, s8, 5
	s_lshl_b32 s44, s8, 6
	s_mov_b32 s45, s8
	v_lshrrev_b32_e32 v222, 6, v0
	v_mul_u32_u24_e32 v218, 0x55f80, v222
	v_lshl_add_u32 v218, v170, 7, v218
	v_lshl_add_u32 v218, v171, 4, v218
	v_mov_b32_e32 v219, 0
	v_mul_u32_u24_e32 v221, 0x2208, v170
	v_lshl_add_u32 v221, v171, 4, v221
	v_mul_u32_u24_e32 v220, 0x420, v222
	v_add_u32_e32 v220, v220, v221
	v_lshl_add_u32 v223, v222, 3, v149
	s_mov_b32 s10, 0xac00
	s_mov_b32 s11, 0
	v_readlane_b32 s8, v254, 61
	v_readlane_b32 s12, v254, 4
	v_readlane_b32 s13, v254, 5
	v_readlane_b32 s14, v254, 6
	v_readlane_b32 s15, v254, 7
	v_readlane_b32 s9, v254, 62
.LBB0_65:
	s_mul_hi_i32 s46, s45, 0x2fa0be83
	s_lshr_b32 s47, s46, 31
	s_ashr_i32 s46, s46, 6
	s_add_i32 s84, s46, s47
	s_mul_i32 s46, s84, 0xffffd500
	s_mul_i32 s47, s84, 0xffffaa00
	s_add_i32 s46, s43, s46
	s_add_i32 s47, s44, s47
	s_and_b32 s48, s46, 0x60
	s_and_b32 s47, s47, 0xffffff00
	s_or_b32 s48, s48, s40
	s_mul_i32 s80, s84, 0x2b0000
	s_or_b32 s48, s48, s47
	s_mul_hi_i32 s49, s84, 0x2b0000
	s_add_u32 s80, s42, s80
	s_addc_u32 s49, s41, s49
	s_ashr_i32 s47, s46, 31
	s_lshl_b64 s[46:47], s[46:47], 2
	s_add_u32 s46, s80, s46
	s_addc_u32 s47, s49, s47
	v_lshl_add_u64 v[2:3], s[46:47], 0, v[218:219]
	global_load_dwordx4 v[22:25], v[2:3], off nt
	v_lshl_add_u64 v[2:3], v[2:3], 0, s[10:11]
	global_load_dwordx4 v[26:29], v[2:3], off nt
	v_lshl_add_u64 v[2:3], v[2:3], 0, s[10:11]
	global_load_dwordx4 v[36:39], v[2:3], off nt
	v_lshl_add_u64 v[2:3], v[2:3], 0, s[10:11]
	global_load_dwordx4 v[40:43], v[2:3], off nt
	v_lshl_add_u64 v[2:3], v[2:3], 0, s[10:11]
	global_load_dwordx4 v[44:47], v[2:3], off nt
	v_lshl_add_u64 v[2:3], v[2:3], 0, s[10:11]
	global_load_dwordx4 v[48:51], v[2:3], off nt
	v_lshl_add_u64 v[2:3], v[2:3], 0, s[10:11]
	global_load_dwordx4 v[52:55], v[2:3], off nt
	v_lshl_add_u64 v[2:3], v[2:3], 0, s[10:11]
	global_load_dwordx4 v[56:59], v[2:3], off nt
	s_ashr_i32 s49, s48, 31
	v_lshl_add_u64 v[4:5], s[48:49], 2, v[10:11]
	s_lshl_b64 s[80:81], s[48:49], 12
	s_add_u32 s46, s51, s80
	s_addc_u32 s47, s52, s81
	s_lshl_b32 s48, s84, 6
	s_ashr_i32 s49, s48, 31
	s_add_u32 s46, s46, s48
	s_addc_u32 s47, s47, s49
	v_lshl_add_u64 v[2:3], s[46:47], 0, v[144:145]
	v_add_u32_e32 v64, 0x400, v223
	v_lshl_add_u64 v[60:61], v[2:3], 0, v[6:7]
	s_add_i32 s45, s45, s8
	s_add_i32 s43, s43, s37
	s_add_i32 s44, s44, s55
	s_cmpk_lt_i32 s45, 0x5600
	s_waitcnt vmcnt(7)
	ds_write2_b32 v220, v22, v23 offset0:0 offset1:1
	ds_write2_b32 v220, v24, v25 offset0:2 offset1:3
	s_waitcnt vmcnt(6)
	ds_write2_b32 v220, v26, v27 offset0:33 offset1:34
	ds_write2_b32 v220, v28, v29 offset0:35 offset1:36
	s_waitcnt vmcnt(5)
	ds_write2_b32 v220, v36, v37 offset0:66 offset1:67
	ds_write2_b32 v220, v38, v39 offset0:68 offset1:69
	s_waitcnt vmcnt(4)
	ds_write2_b32 v220, v40, v41 offset0:99 offset1:100
	ds_write2_b32 v220, v42, v43 offset0:101 offset1:102
	s_waitcnt vmcnt(3)
	ds_write2_b32 v220, v44, v45 offset0:132 offset1:133
	ds_write2_b32 v220, v46, v47 offset0:134 offset1:135
	s_waitcnt vmcnt(2)
	ds_write2_b32 v220, v48, v49 offset0:165 offset1:166
	ds_write2_b32 v220, v50, v51 offset0:167 offset1:168
	s_waitcnt vmcnt(1)
	ds_write2_b32 v220, v52, v53 offset0:198 offset1:199
	ds_write2_b32 v220, v54, v55 offset0:200 offset1:201
	s_waitcnt vmcnt(0)
	ds_write2_b32 v220, v56, v57 offset0:231 offset1:232
	ds_write2_b32 v220, v58, v59 offset0:233 offset1:234
	s_waitcnt lgkmcnt(0)
	s_barrier
	global_load_dword v13, v[4:5], off
	ds_read2_b32 v[26:27], v223 offset1:16
	ds_read2_b32 v[28:29], v223 offset0:33 offset1:49
	ds_read2_b32 v[36:37], v223 offset0:66 offset1:82
	ds_read2_b32 v[38:39], v223 offset0:99 offset1:115
	ds_read2_b32 v[40:41], v223 offset0:132 offset1:148
	ds_read2_b32 v[42:43], v223 offset0:165 offset1:181
	ds_read2_b32 v[44:45], v223 offset0:198 offset1:214
	ds_read2_b32 v[46:47], v223 offset0:231 offset1:247
	ds_read2_b32 v[48:49], v64 offset0:8 offset1:24
	ds_read2_b32 v[50:51], v64 offset0:41 offset1:57
	ds_read2_b32 v[52:53], v64 offset0:74 offset1:90
	ds_read2_b32 v[54:55], v64 offset0:107 offset1:123
	ds_read2_b32 v[56:57], v64 offset0:140 offset1:156
	ds_read2_b32 v[58:59], v64 offset0:173 offset1:189
	ds_read2_b32 v[62:63], v64 offset0:206 offset1:222
	ds_read2_b32 v[64:65], v64 offset0:239 offset1:255
	s_waitcnt lgkmcnt(14)
	v_mov_b32_e32 v22, v26
	v_mov_b32_e32 v24, v28
	s_waitcnt lgkmcnt(10)
	v_mov_b32_e32 v25, v42
	v_mov_b32_e32 v68, v38
	s_waitcnt lgkmcnt(8)
	v_mov_b32_e32 v69, v46
	s_waitcnt lgkmcnt(6)
	v_mov_b32_e32 v72, v50
	s_waitcnt lgkmcnt(2)
	v_mov_b32_e32 v73, v58
	v_mov_b32_e32 v74, v52
	s_waitcnt lgkmcnt(1)
	v_mov_b32_e32 v75, v62
	v_mov_b32_e32 v76, v54
	s_waitcnt lgkmcnt(0)
	v_mov_b32_e32 v77, v64
	v_mov_b32_e32 v23, v40
	v_mov_b32_e32 v66, v36
	v_mov_b32_e32 v67, v44
	v_mov_b32_e32 v70, v48
	v_mov_b32_e32 v71, v56
	v_mov_b32_e32 v40, v27
	v_mov_b32_e32 v42, v29
	v_mov_b32_e32 v44, v37
	v_mov_b32_e32 v46, v39
	v_mov_b32_e32 v56, v49
	v_mov_b32_e32 v58, v51
	v_mov_b32_e32 v62, v53
	v_mov_b32_e32 v64, v55
	s_waitcnt vmcnt(0)
	v_div_scale_f32 v15, s[46:47], v13, v13, s90
	v_rcp_f32_e32 v19, v15
	v_div_scale_f32 v17, vcc, s90, v13, s90
	v_fma_f32 v21, -v15, v19, 1.0
	v_fmac_f32_e32 v19, v21, v19
	v_mul_f32_e32 v21, v17, v19
	v_fma_f32 v26, -v15, v21, v17
	v_fmac_f32_e32 v21, v26, v19
	v_fma_f32 v15, -v15, v21, v17
	v_div_fmas_f32 v15, v15, v19, v21
	v_div_fixup_f32 v15, v15, v13, s90
	v_cmp_lt_f32_e32 vcc, 0, v13
	s_nop 1
	v_cndmask_b32_e32 v26, 0, v15, vcc
	v_pk_fma_f32 v[24:25], v[24:25], v[26:27], s[78:79] op_sel_hi:[1,0,0]
	v_pk_fma_f32 v[68:69], v[68:69], v[26:27], s[78:79] op_sel_hi:[1,0,0]
	v_pk_fma_f32 v[72:73], v[72:73], v[26:27], s[78:79] op_sel_hi:[1,0,0]
	v_pk_fma_f32 v[74:75], v[74:75], v[26:27], s[78:79] op_sel_hi:[1,0,0]
	v_pk_fma_f32 v[76:77], v[76:77], v[26:27], s[78:79] op_sel_hi:[1,0,0]
	v_pk_fma_f32 v[22:23], v[22:23], v[26:27], s[78:79] op_sel_hi:[1,0,0]
	v_pk_fma_f32 v[66:67], v[66:67], v[26:27], s[78:79] op_sel_hi:[1,0,0]
	v_pk_fma_f32 v[70:71], v[70:71], v[26:27], s[78:79] op_sel_hi:[1,0,0]
	v_lshlrev_b32_e32 v13, 8, v25
	v_lshlrev_b32_e32 v15, 8, v24
	v_lshlrev_b32_e32 v21, 24, v69
	v_lshlrev_b32_e32 v24, 24, v68
	v_lshlrev_b32_e32 v25, 8, v73
	v_lshlrev_b32_e32 v26, 8, v72
	v_lshlrev_b32_e32 v28, 16, v75
	v_lshlrev_b32_e32 v35, 16, v74
	v_lshlrev_b32_e32 v36, 24, v77
	v_lshlrev_b32_e32 v38, 24, v76
	v_lshlrev_b32_e32 v17, 16, v67
	v_lshlrev_b32_e32 v19, 16, v66
	v_and_b32_e32 v13, 0xff00, v13
	v_and_b32_e32 v15, 0xff00, v15
	v_or_b32_sdwa v21, v21, v23 dst_sel:DWORD dst_unused:UNUSED_PAD src0_sel:DWORD src1_sel:BYTE_0
	v_or_b32_sdwa v22, v24, v22 dst_sel:DWORD dst_unused:UNUSED_PAD src0_sel:DWORD src1_sel:BYTE_0
	v_and_b32_e32 v23, 0xff00, v25
	v_and_b32_e32 v24, 0xff00, v26
	v_and_b32_e32 v25, 0xff0000, v28
	v_and_b32_e32 v26, 0xff0000, v35
	v_or_b32_sdwa v28, v36, v71 dst_sel:DWORD dst_unused:UNUSED_PAD src0_sel:DWORD src1_sel:BYTE_0
	v_or_b32_sdwa v35, v38, v70 dst_sel:DWORD dst_unused:UNUSED_PAD src0_sel:DWORD src1_sel:BYTE_0
	v_and_b32_e32 v17, 0xff0000, v17
	v_and_b32_e32 v19, 0xff0000, v19
	v_or_b32_e32 v13, v21, v13
	v_or_b32_e32 v15, v22, v15
	v_or_b32_e32 v21, v28, v23
	v_or_b32_e32 v24, v35, v24
	v_or_b32_e32 v23, v13, v17
	v_or_b32_e32 v22, v15, v19
	v_or_b32_e32 v25, v21, v25
	v_or_b32_e32 v24, v24, v26
	global_store_dwordx4 v[60:61], v[22:25], off
	global_load_dword v4, v[4:5], off offset:64
	s_nop 0
	v_lshl_add_u64 v[22:23], v[2:3], 0, v[146:147]
	s_waitcnt vmcnt(0)
	v_div_scale_f32 v2, s[46:47], v4, v4, s90
	v_rcp_f32_e32 v5, v2
	v_div_scale_f32 v3, vcc, s90, v4, s90
	v_fma_f32 v13, -v2, v5, 1.0
	v_fmac_f32_e32 v5, v13, v5
	v_mul_f32_e32 v13, v3, v5
	v_fma_f32 v15, -v2, v13, v3
	v_fmac_f32_e32 v13, v15, v5
	v_fma_f32 v2, -v2, v13, v3
	v_div_fmas_f32 v2, v2, v5, v13
	v_div_fixup_f32 v2, v2, v4, s90
	v_cmp_lt_f32_e32 vcc, 0, v4
	s_nop 1
	v_cndmask_b32_e32 v2, 0, v2, vcc
	v_pk_fma_f32 v[4:5], v[40:41], v[2:3], s[78:79] op_sel_hi:[1,0,0]
	v_pk_fma_f32 v[24:25], v[42:43], v[2:3], s[78:79] op_sel_hi:[1,0,0]
	v_pk_fma_f32 v[26:27], v[44:45], v[2:3], s[78:79] op_sel_hi:[1,0,0]
	v_pk_fma_f32 v[28:29], v[46:47], v[2:3], s[78:79] op_sel_hi:[1,0,0]
	v_pk_fma_f32 v[36:37], v[56:57], v[2:3], s[78:79] op_sel_hi:[1,0,0]
	v_pk_fma_f32 v[38:39], v[58:59], v[2:3], s[78:79] op_sel_hi:[1,0,0]
	v_pk_fma_f32 v[40:41], v[62:63], v[2:3], s[78:79] op_sel_hi:[1,0,0]
	v_pk_fma_f32 v[2:3], v[64:65], v[2:3], s[78:79] op_sel_hi:[1,0,0]
	v_lshlrev_b32_e32 v13, 8, v25
	v_lshlrev_b32_e32 v15, 8, v24
	v_lshlrev_b32_e32 v19, 16, v26
	v_lshlrev_b32_e32 v21, 24, v29
	v_lshlrev_b32_e32 v24, 24, v28
	v_lshlrev_b32_e32 v25, 8, v39
	v_lshlrev_b32_e32 v26, 8, v38
	v_lshlrev_b32_e32 v3, 24, v3
	v_lshlrev_b32_e32 v2, 24, v2
	v_lshlrev_b32_e32 v17, 16, v27
	v_lshlrev_b32_e32 v27, 16, v41
	v_lshlrev_b32_e32 v28, 16, v40
	v_and_b32_e32 v13, 0xff00, v13
	v_and_b32_e32 v15, 0xff00, v15
	v_or_b32_sdwa v5, v21, v5 dst_sel:DWORD dst_unused:UNUSED_PAD src0_sel:DWORD src1_sel:BYTE_0
	v_or_b32_sdwa v4, v24, v4 dst_sel:DWORD dst_unused:UNUSED_PAD src0_sel:DWORD src1_sel:BYTE_0
	v_and_b32_e32 v21, 0xff00, v25
	v_and_b32_e32 v24, 0xff00, v26
	v_or_b32_sdwa v3, v3, v37 dst_sel:DWORD dst_unused:UNUSED_PAD src0_sel:DWORD src1_sel:BYTE_0
	v_or_b32_sdwa v2, v2, v36 dst_sel:DWORD dst_unused:UNUSED_PAD src0_sel:DWORD src1_sel:BYTE_0
	v_and_b32_e32 v17, 0xff0000, v17
	v_and_b32_e32 v19, 0xff0000, v19
	v_and_b32_e32 v25, 0xff0000, v27
	v_and_b32_e32 v26, 0xff0000, v28
	v_or_b32_e32 v5, v5, v13
	v_or_b32_e32 v4, v4, v15
	v_or_b32_e32 v13, v3, v21
	v_or_b32_e32 v15, v2, v24
	v_or_b32_e32 v3, v5, v17
	v_or_b32_e32 v2, v4, v19
	v_or_b32_e32 v5, v13, v25
	v_or_b32_e32 v4, v15, v26
	global_store_dwordx4 v[22:23], v[2:5], off
	s_waitcnt lgkmcnt(0)
	s_barrier
	s_cbranch_scc1 .LBB0_65
	s_branch .LBB0_7
